# gate/up epilogue: the eight 16-byte act stores per lane are write-through (sc1) so the L2 write-back at the following grid barrier has little left to flush
# baseline (speedup 1.0000x reference)
.LBB0_1605:
	s_waitcnt lgkmcnt(0)
	v_pk_mul_f32 v[134:135], v[134:135], v[0:1] op_sel_hi:[1,0]
	v_pk_mul_f32 v[130:131], v[130:131], v[0:1] op_sel_hi:[1,0]
	v_pk_mul_f32 v[144:145], v[134:135], s[22:23] op_sel_hi:[1,0]
	v_pk_mul_f32 v[132:133], v[132:133], v[0:1] op_sel_hi:[1,0]
	v_exp_f32_e32 v144, v144
	v_exp_f32_e32 v145, v145
	v_pk_mul_f32 v[126:127], v[126:127], v[0:1] op_sel_hi:[1,0]
	v_pk_mul_f32 v[122:123], v[122:123], v[0:1] op_sel_hi:[1,0]
	v_pk_mul_f32 v[124:125], v[124:125], v[0:1] op_sel_hi:[1,0]
	v_pk_add_f32 v[144:145], v[144:145], 1.0 op_sel_hi:[1,0]
	v_lshl_or_b32 v142, s56, 7, v209
	v_rcp_f32_e32 v144, v144
	v_rcp_f32_e32 v145, v145
	v_ashrrev_i32_e32 v143, 31, v142
	v_pk_mul_f32 v[118:119], v[118:119], v[0:1] op_sel:[0,1]
	v_pk_mul_f32 v[114:115], v[114:115], v[0:1] op_sel:[0,1]
	v_pk_mul_f32 v[134:135], v[134:135], v[144:145]
	v_pk_mul_f32 v[116:117], v[116:117], v[0:1] op_sel:[0,1]
	v_pk_mul_f32 v[130:131], v[130:131], v[134:135]
	v_pk_mul_f32 v[134:135], v[136:137], v[0:1] op_sel_hi:[1,0]
	v_pk_mul_f32 v[110:111], v[110:111], v[0:1] op_sel:[0,1]
	v_pk_mul_f32 v[136:137], v[134:135], s[22:23] op_sel_hi:[1,0]
	v_pk_mul_f32 v[106:107], v[106:107], v[0:1] op_sel:[0,1]
	v_exp_f32_e32 v136, v136
	v_exp_f32_e32 v137, v137
	v_pk_mul_f32 v[98:99], v[98:99], v[2:3] op_sel_hi:[1,0]
	v_pk_mul_f32 v[100:101], v[100:101], v[2:3] op_sel_hi:[1,0]
	v_pk_mul_f32 v[94:95], v[94:95], v[2:3] op_sel_hi:[1,0]
	v_pk_add_f32 v[136:137], v[136:137], 1.0 op_sel_hi:[1,0]
	v_pk_mul_f32 v[90:91], v[90:91], v[2:3] op_sel_hi:[1,0]
	v_rcp_f32_e32 v136, v136
	v_rcp_f32_e32 v137, v137
	v_pk_mul_f32 v[92:93], v[92:93], v[2:3] op_sel_hi:[1,0]
	v_pk_mul_f32 v[62:63], v[62:63], v[4:5] op_sel_hi:[1,0]
	v_pk_mul_f32 v[58:59], v[58:59], v[4:5] op_sel_hi:[1,0]
	v_pk_mul_f32 v[134:135], v[134:135], v[136:137]
	v_pk_mul_f32 v[60:61], v[60:61], v[4:5] op_sel_hi:[1,0]
	v_pk_mul_f32 v[132:133], v[132:133], v[134:135]
	v_pk_mul_f32 v[134:135], v[126:127], s[22:23] op_sel_hi:[1,0]
	v_pk_mul_f32 v[26:27], v[26:27], v[6:7] op_sel_hi:[1,0]
	v_exp_f32_e32 v134, v134
	v_exp_f32_e32 v135, v135
	v_pk_mul_f32 v[28:29], v[28:29], v[6:7] op_sel_hi:[1,0]
	s_andn2_b64 vcc, exec, s[40:41]
	v_pk_add_f32 v[134:135], v[134:135], 1.0 op_sel_hi:[1,0]
	s_nop 0
	v_rcp_f32_e32 v134, v134
	v_rcp_f32_e32 v135, v135
	s_nop 0
	v_pk_mul_f32 v[126:127], v[126:127], v[134:135]
	s_nop 0
	v_pk_mul_f32 v[122:123], v[122:123], v[126:127]
	v_pk_mul_f32 v[126:127], v[128:129], v[0:1] op_sel_hi:[1,0]
	s_nop 0
	v_pk_mul_f32 v[128:129], v[126:127], s[22:23] op_sel_hi:[1,0]
	s_nop 0
	v_exp_f32_e32 v128, v128
	v_exp_f32_e32 v129, v129
	s_nop 0
	v_pk_add_f32 v[128:129], v[128:129], 1.0 op_sel_hi:[1,0]
	s_nop 0
	v_rcp_f32_e32 v128, v128
	v_rcp_f32_e32 v129, v129
	s_nop 0
	v_pk_mul_f32 v[126:127], v[126:127], v[128:129]
	s_nop 0
	v_pk_mul_f32 v[124:125], v[124:125], v[126:127]
	v_cvt_pk_bf16_f32 v126, v130, v131
	v_cvt_pk_bf16_f32 v127, v132, v133
	v_cvt_pk_bf16_f32 v128, v122, v123
	v_mov_b64_e32 v[122:123], s[2:3]
	v_mad_u64_u32 v[130:131], s[14:15], v182, s91, v[122:123]
	v_cvt_pk_bf16_f32 v129, v124, v125
	v_mov_b32_e32 v124, v131
	v_mad_u64_u32 v[124:125], s[14:15], v183, s91, v[124:125]
	v_mov_b32_e32 v131, v124
	v_lshlrev_b64 v[124:125], 1, v[142:143]
	v_lshl_add_u64 v[130:131], v[130:131], 0, v[124:125]
	global_store_dwordx4 v[130:131], v[126:129], off sc1
	s_nop 1
	v_pk_mul_f32 v[126:127], v[118:119], s[22:23] op_sel_hi:[1,0]
	s_nop 0
	v_exp_f32_e32 v126, v126
	v_exp_f32_e32 v127, v127
	s_nop 0
	v_pk_add_f32 v[126:127], v[126:127], 1.0 op_sel_hi:[1,0]
	s_nop 0
	v_rcp_f32_e32 v126, v126
	v_rcp_f32_e32 v127, v127
	s_nop 0
	v_pk_mul_f32 v[118:119], v[118:119], v[126:127]
	s_nop 0
	v_pk_mul_f32 v[114:115], v[114:115], v[118:119]
	v_pk_mul_f32 v[118:119], v[120:121], v[0:1] op_sel:[0,1]
	s_nop 0
	v_pk_mul_f32 v[120:121], v[118:119], s[22:23] op_sel_hi:[1,0]
	s_nop 0
	v_exp_f32_e32 v120, v120
	v_exp_f32_e32 v121, v121
	s_nop 0
	v_pk_add_f32 v[120:121], v[120:121], 1.0 op_sel_hi:[1,0]
	s_nop 0
	v_rcp_f32_e32 v120, v120
	v_rcp_f32_e32 v121, v121
	s_nop 0
	v_pk_mul_f32 v[118:119], v[118:119], v[120:121]
	s_nop 0
	v_pk_mul_f32 v[116:117], v[116:117], v[118:119]
	v_pk_mul_f32 v[118:119], v[110:111], s[22:23] op_sel_hi:[1,0]
	s_nop 0
	v_exp_f32_e32 v118, v118
	v_exp_f32_e32 v119, v119
	s_nop 0
	v_pk_add_f32 v[118:119], v[118:119], 1.0 op_sel_hi:[1,0]
	s_nop 0
	v_rcp_f32_e32 v118, v118
	v_rcp_f32_e32 v119, v119
	s_nop 0
	v_pk_mul_f32 v[110:111], v[110:111], v[118:119]
	s_nop 0
	v_pk_mul_f32 v[110:111], v[106:107], v[110:111]
	v_pk_mul_f32 v[106:107], v[112:113], v[0:1] op_sel:[0,1]
	v_pk_mul_f32 v[0:1], v[108:109], v[0:1] op_sel:[0,1]
	v_pk_mul_f32 v[108:109], v[106:107], s[22:23] op_sel_hi:[1,0]
	s_nop 0
	v_exp_f32_e32 v108, v108
	v_exp_f32_e32 v109, v109
	s_nop 0
	v_pk_add_f32 v[108:109], v[108:109], 1.0 op_sel_hi:[1,0]
	s_nop 0
	v_rcp_f32_e32 v108, v108
	v_rcp_f32_e32 v109, v109
	s_nop 0
	v_pk_mul_f32 v[106:107], v[106:107], v[108:109]
	s_nop 0
	v_pk_mul_f32 v[0:1], v[0:1], v[106:107]
	v_cvt_pk_bf16_f32 v106, v114, v115
	v_cvt_pk_bf16_f32 v107, v116, v117
	v_cvt_pk_bf16_f32 v108, v110, v111
	s_nop 0
	v_cvt_pk_bf16_f32 v109, v0, v1
	v_mad_u64_u32 v[0:1], s[14:15], v180, s91, v[122:123]
	v_mov_b32_e32 v110, v1
	v_mad_u64_u32 v[110:111], s[14:15], v181, s91, v[110:111]
	v_mov_b32_e32 v1, v110
	v_lshl_add_u64 v[0:1], v[0:1], 0, v[124:125]
	global_store_dwordx4 v[0:1], v[106:109], off sc1
	v_pk_mul_f32 v[0:1], v[102:103], v[2:3] op_sel_hi:[1,0]
	s_nop 0
	v_pk_mul_f32 v[102:103], v[0:1], s[22:23] op_sel_hi:[1,0]
	s_nop 0
	v_exp_f32_e32 v102, v102
	v_exp_f32_e32 v103, v103
	s_nop 0
	v_pk_add_f32 v[102:103], v[102:103], 1.0 op_sel_hi:[1,0]
	s_nop 0
	v_rcp_f32_e32 v102, v102
	v_rcp_f32_e32 v103, v103
	s_nop 0
	v_pk_mul_f32 v[0:1], v[0:1], v[102:103]
	s_nop 0
	v_pk_mul_f32 v[0:1], v[98:99], v[0:1]
	v_pk_mul_f32 v[98:99], v[104:105], v[2:3] op_sel_hi:[1,0]
	s_nop 0
	v_pk_mul_f32 v[102:103], v[98:99], s[22:23] op_sel_hi:[1,0]
	s_nop 0
	v_exp_f32_e32 v102, v102
	v_exp_f32_e32 v103, v103
	s_nop 0
	v_pk_add_f32 v[102:103], v[102:103], 1.0 op_sel_hi:[1,0]
	s_nop 0
	v_rcp_f32_e32 v102, v102
	v_rcp_f32_e32 v103, v103
	s_nop 0
	v_pk_mul_f32 v[98:99], v[98:99], v[102:103]
	s_nop 0
	v_pk_mul_f32 v[98:99], v[100:101], v[98:99]
	v_pk_mul_f32 v[100:101], v[94:95], s[22:23] op_sel_hi:[1,0]
	s_nop 0
	v_exp_f32_e32 v100, v100
	v_exp_f32_e32 v101, v101
	s_nop 0
	v_pk_add_f32 v[100:101], v[100:101], 1.0 op_sel_hi:[1,0]
	s_nop 0
	v_rcp_f32_e32 v100, v100
	v_rcp_f32_e32 v101, v101
	s_nop 0
	v_pk_mul_f32 v[94:95], v[94:95], v[100:101]
	s_nop 0
	v_pk_mul_f32 v[94:95], v[90:91], v[94:95]
	v_pk_mul_f32 v[90:91], v[96:97], v[2:3] op_sel_hi:[1,0]
	s_nop 0
	v_pk_mul_f32 v[96:97], v[90:91], s[22:23] op_sel_hi:[1,0]
	s_nop 0
	v_exp_f32_e32 v96, v96
	v_exp_f32_e32 v97, v97
	s_nop 0
	v_pk_add_f32 v[96:97], v[96:97], 1.0 op_sel_hi:[1,0]
	s_nop 0
	v_rcp_f32_e32 v96, v96
	v_rcp_f32_e32 v97, v97
	s_nop 0
	v_pk_mul_f32 v[90:91], v[90:91], v[96:97]
	s_nop 0
	v_pk_mul_f32 v[96:97], v[92:93], v[90:91]
	v_cvt_pk_bf16_f32 v90, v0, v1
	v_mad_u64_u32 v[0:1], s[14:15], v178, s91, v[122:123]
	v_mov_b32_e32 v2, v1
	v_cvt_pk_bf16_f32 v91, v98, v99
	v_cvt_pk_bf16_f32 v92, v94, v95
	v_mad_u64_u32 v[94:95], s[14:15], v179, s91, v[2:3]
	v_mov_b32_e32 v1, v94
	v_lshl_add_u64 v[0:1], v[0:1], 0, v[124:125]
	v_cvt_pk_bf16_f32 v93, v96, v97
	global_store_dwordx4 v[0:1], v[90:93], off sc1
	v_mov_b32_e32 v0, v3
	v_pk_mul_f32 v[2:3], v[86:87], v[0:1] op_sel_hi:[1,0]
	v_pk_mul_f32 v[82:83], v[82:83], v[0:1] op_sel_hi:[1,0]
	v_pk_mul_f32 v[86:87], v[2:3], s[22:23] op_sel_hi:[1,0]
	v_pk_mul_f32 v[84:85], v[84:85], v[0:1] op_sel_hi:[1,0]
	v_exp_f32_e32 v86, v86
	v_exp_f32_e32 v87, v87
	v_pk_mul_f32 v[78:79], v[78:79], v[0:1] op_sel_hi:[1,0]
	v_pk_mul_f32 v[74:75], v[74:75], v[0:1] op_sel_hi:[1,0]
	v_pk_add_f32 v[86:87], v[86:87], 1.0 op_sel_hi:[1,0]
	s_nop 0
	v_rcp_f32_e32 v86, v86
	v_rcp_f32_e32 v87, v87
	s_nop 0
	v_pk_mul_f32 v[2:3], v[2:3], v[86:87]
	s_nop 0
	v_pk_mul_f32 v[2:3], v[82:83], v[2:3]
	v_pk_mul_f32 v[82:83], v[88:89], v[0:1] op_sel_hi:[1,0]
	s_nop 0
	v_pk_mul_f32 v[86:87], v[82:83], s[22:23] op_sel_hi:[1,0]
	s_nop 0
	v_exp_f32_e32 v86, v86
	v_exp_f32_e32 v87, v87
	s_nop 0
	v_pk_add_f32 v[86:87], v[86:87], 1.0 op_sel_hi:[1,0]
	s_nop 0
	v_rcp_f32_e32 v86, v86
	v_rcp_f32_e32 v87, v87
	s_nop 0
	v_pk_mul_f32 v[82:83], v[82:83], v[86:87]
	s_nop 0
	v_pk_mul_f32 v[82:83], v[84:85], v[82:83]
	v_pk_mul_f32 v[84:85], v[78:79], s[22:23] op_sel_hi:[1,0]
	s_nop 0
	v_exp_f32_e32 v84, v84
	v_exp_f32_e32 v85, v85
	s_nop 0
	v_pk_add_f32 v[84:85], v[84:85], 1.0 op_sel_hi:[1,0]
	s_nop 0
	v_rcp_f32_e32 v84, v84
	v_rcp_f32_e32 v85, v85
	s_nop 0
	v_pk_mul_f32 v[78:79], v[78:79], v[84:85]
	s_nop 0
	v_pk_mul_f32 v[74:75], v[74:75], v[78:79]
	v_pk_mul_f32 v[78:79], v[80:81], v[0:1] op_sel_hi:[1,0]
	v_pk_mul_f32 v[0:1], v[76:77], v[0:1] op_sel_hi:[1,0]
	v_pk_mul_f32 v[76:77], v[78:79], s[22:23] op_sel_hi:[1,0]
	s_nop 0
	v_exp_f32_e32 v76, v76
	v_exp_f32_e32 v77, v77
	s_nop 0
	v_pk_add_f32 v[76:77], v[76:77], 1.0 op_sel_hi:[1,0]
	s_nop 0
	v_rcp_f32_e32 v76, v76
	v_rcp_f32_e32 v77, v77
	s_nop 0
	v_pk_mul_f32 v[76:77], v[78:79], v[76:77]
	s_nop 0
	v_pk_mul_f32 v[76:77], v[0:1], v[76:77]
	v_cvt_pk_bf16_f32 v0, v2, v3
	v_cvt_pk_bf16_f32 v1, v82, v83
	v_cvt_pk_bf16_f32 v2, v74, v75
	v_mad_u64_u32 v[74:75], s[14:15], v176, s91, v[122:123]
	v_cvt_pk_bf16_f32 v3, v76, v77
	v_mov_b32_e32 v76, v75
	v_mad_u64_u32 v[76:77], s[14:15], v177, s91, v[76:77]
	v_mov_b32_e32 v75, v76
	v_lshl_add_u64 v[74:75], v[74:75], 0, v[124:125]
	global_store_dwordx4 v[74:75], v[0:3], off sc1
	s_nop 1
	v_pk_mul_f32 v[0:1], v[70:71], v[4:5] op_sel_hi:[1,0]
	v_pk_mul_f32 v[2:3], v[66:67], v[4:5] op_sel_hi:[1,0]
	v_pk_mul_f32 v[66:67], v[0:1], s[22:23] op_sel_hi:[1,0]
	s_nop 0
	v_exp_f32_e32 v66, v66
	v_exp_f32_e32 v67, v67
	s_nop 0
	v_pk_add_f32 v[66:67], v[66:67], 1.0 op_sel_hi:[1,0]
	s_nop 0
	v_rcp_f32_e32 v66, v66
	v_rcp_f32_e32 v67, v67
	s_nop 0
	v_pk_mul_f32 v[0:1], v[0:1], v[66:67]
	s_nop 0
	v_pk_mul_f32 v[0:1], v[2:3], v[0:1]
	v_pk_mul_f32 v[2:3], v[72:73], v[4:5] op_sel_hi:[1,0]
	v_pk_mul_f32 v[66:67], v[68:69], v[4:5] op_sel_hi:[1,0]
	v_pk_mul_f32 v[68:69], v[2:3], s[22:23] op_sel_hi:[1,0]
	v_cvt_pk_bf16_f32 v0, v0, v1
	s_nop 0
	v_exp_f32_e32 v68, v68
	v_exp_f32_e32 v69, v69
	s_nop 0
	v_pk_add_f32 v[68:69], v[68:69], 1.0 op_sel_hi:[1,0]
	s_nop 0
	v_rcp_f32_e32 v68, v68
	v_rcp_f32_e32 v69, v69
	s_nop 0
	v_pk_mul_f32 v[2:3], v[2:3], v[68:69]
	s_nop 0
	v_pk_mul_f32 v[2:3], v[66:67], v[2:3]
	v_pk_mul_f32 v[66:67], v[62:63], s[22:23] op_sel_hi:[1,0]
	v_cvt_pk_bf16_f32 v1, v2, v3
	s_nop 0
	v_exp_f32_e32 v66, v66
	v_exp_f32_e32 v67, v67
	s_nop 0
	v_pk_add_f32 v[66:67], v[66:67], 1.0 op_sel_hi:[1,0]
	s_nop 0
	v_rcp_f32_e32 v66, v66
	v_rcp_f32_e32 v67, v67
	s_nop 0
	v_pk_mul_f32 v[62:63], v[62:63], v[66:67]
	s_nop 0
	v_pk_mul_f32 v[58:59], v[58:59], v[62:63]
	v_pk_mul_f32 v[62:63], v[64:65], v[4:5] op_sel_hi:[1,0]
	v_cvt_pk_bf16_f32 v2, v58, v59
	v_mad_u64_u32 v[58:59], s[14:15], v140, s91, v[122:123]
	v_pk_mul_f32 v[64:65], v[62:63], s[22:23] op_sel_hi:[1,0]
	v_mov_b32_e32 v4, v59
	v_exp_f32_e32 v64, v64
	v_exp_f32_e32 v65, v65
	s_nop 0
	v_pk_add_f32 v[64:65], v[64:65], 1.0 op_sel_hi:[1,0]
	s_nop 0
	v_rcp_f32_e32 v64, v64
	v_rcp_f32_e32 v65, v65
	s_nop 0
	v_pk_mul_f32 v[62:63], v[62:63], v[64:65]
	s_nop 0
	v_pk_mul_f32 v[60:61], v[60:61], v[62:63]
	s_nop 0
	v_cvt_pk_bf16_f32 v3, v60, v61
	v_mad_u64_u32 v[60:61], s[14:15], v141, s91, v[4:5]
	v_mov_b32_e32 v59, v60
	v_lshl_add_u64 v[58:59], v[58:59], 0, v[124:125]
	global_store_dwordx4 v[58:59], v[0:3], off sc1
	s_nop 1
	v_mov_b32_e32 v0, v5
	v_pk_mul_f32 v[2:3], v[54:55], v[0:1] op_sel_hi:[1,0]
	v_pk_mul_f32 v[4:5], v[50:51], v[0:1] op_sel_hi:[1,0]
	v_pk_mul_f32 v[50:51], v[2:3], s[22:23] op_sel_hi:[1,0]
	v_pk_mul_f32 v[46:47], v[46:47], v[0:1] op_sel_hi:[1,0]
	v_exp_f32_e32 v50, v50
	v_exp_f32_e32 v51, v51
	v_pk_mul_f32 v[42:43], v[42:43], v[0:1] op_sel_hi:[1,0]
	v_pk_add_f32 v[50:51], v[50:51], 1.0 op_sel_hi:[1,0]
	s_nop 0
	v_rcp_f32_e32 v50, v50
	v_rcp_f32_e32 v51, v51
	s_nop 0
	v_pk_mul_f32 v[2:3], v[2:3], v[50:51]
	s_nop 0
	v_pk_mul_f32 v[2:3], v[4:5], v[2:3]
	v_pk_mul_f32 v[4:5], v[56:57], v[0:1] op_sel_hi:[1,0]
	v_pk_mul_f32 v[50:51], v[52:53], v[0:1] op_sel_hi:[1,0]
	v_pk_mul_f32 v[52:53], v[4:5], s[22:23] op_sel_hi:[1,0]
	s_nop 0
	v_exp_f32_e32 v52, v52
	v_exp_f32_e32 v53, v53
	s_nop 0
	v_pk_add_f32 v[52:53], v[52:53], 1.0 op_sel_hi:[1,0]
	s_nop 0
	v_rcp_f32_e32 v52, v52
	v_rcp_f32_e32 v53, v53
	s_nop 0
	v_pk_mul_f32 v[4:5], v[4:5], v[52:53]
	s_nop 0
	v_pk_mul_f32 v[4:5], v[50:51], v[4:5]
	v_pk_mul_f32 v[50:51], v[46:47], s[22:23] op_sel_hi:[1,0]
	s_nop 0
	v_exp_f32_e32 v50, v50
	v_exp_f32_e32 v51, v51
	s_nop 0
	v_pk_add_f32 v[50:51], v[50:51], 1.0 op_sel_hi:[1,0]
	s_nop 0
	v_rcp_f32_e32 v50, v50
	v_rcp_f32_e32 v51, v51
	s_nop 0
	v_pk_mul_f32 v[46:47], v[46:47], v[50:51]
	s_nop 0
	v_pk_mul_f32 v[42:43], v[42:43], v[46:47]
	v_pk_mul_f32 v[46:47], v[48:49], v[0:1] op_sel_hi:[1,0]
	v_pk_mul_f32 v[0:1], v[44:45], v[0:1] op_sel_hi:[1,0]
	v_pk_mul_f32 v[44:45], v[46:47], s[22:23] op_sel_hi:[1,0]
	s_nop 0
	v_exp_f32_e32 v44, v44
	v_exp_f32_e32 v45, v45
	s_nop 0
	v_pk_add_f32 v[44:45], v[44:45], 1.0 op_sel_hi:[1,0]
	s_nop 0
	v_rcp_f32_e32 v44, v44
	v_rcp_f32_e32 v45, v45
	s_nop 0
	v_pk_mul_f32 v[44:45], v[46:47], v[44:45]
	v_add_u32_e32 v46, 16, v138
	v_pk_mul_f32 v[44:45], v[0:1], v[44:45]
	v_cvt_pk_bf16_f32 v0, v2, v3
	v_cvt_pk_bf16_f32 v1, v4, v5
	v_mad_i64_i32 v[4:5], s[14:15], v46, s91, v[122:123]
	v_lshl_add_u64 v[4:5], v[4:5], 0, v[124:125]
	v_cvt_pk_bf16_f32 v2, v42, v43
	v_cvt_pk_bf16_f32 v3, v44, v45
	global_store_dwordx4 v[4:5], v[0:3], off sc1
	s_nop 1
	v_pk_mul_f32 v[0:1], v[38:39], v[6:7] op_sel_hi:[1,0]
	v_pk_mul_f32 v[2:3], v[34:35], v[6:7] op_sel_hi:[1,0]
	v_pk_mul_f32 v[4:5], v[0:1], s[22:23] op_sel_hi:[1,0]
	s_nop 0
	v_exp_f32_e32 v4, v4
	v_exp_f32_e32 v5, v5
	s_nop 0
	v_pk_add_f32 v[4:5], v[4:5], 1.0 op_sel_hi:[1,0]
	s_nop 0
	v_rcp_f32_e32 v4, v4
	v_rcp_f32_e32 v5, v5
	s_nop 0
	v_pk_mul_f32 v[0:1], v[0:1], v[4:5]
	s_nop 0
	v_pk_mul_f32 v[0:1], v[2:3], v[0:1]
	v_pk_mul_f32 v[2:3], v[40:41], v[6:7] op_sel_hi:[1,0]
	v_pk_mul_f32 v[4:5], v[36:37], v[6:7] op_sel_hi:[1,0]
	v_pk_mul_f32 v[34:35], v[2:3], s[22:23] op_sel_hi:[1,0]
	v_cvt_pk_bf16_f32 v0, v0, v1
	s_nop 0
	v_exp_f32_e32 v34, v34
	v_exp_f32_e32 v35, v35
	s_nop 0
	v_pk_add_f32 v[34:35], v[34:35], 1.0 op_sel_hi:[1,0]
	s_nop 0
	v_rcp_f32_e32 v34, v34
	v_rcp_f32_e32 v35, v35
	s_nop 0
	v_pk_mul_f32 v[2:3], v[2:3], v[34:35]
	s_nop 0
	v_pk_mul_f32 v[2:3], v[4:5], v[2:3]
	v_pk_mul_f32 v[4:5], v[30:31], v[6:7] op_sel_hi:[1,0]
	v_cvt_pk_bf16_f32 v1, v2, v3
	s_nop 0
	v_pk_mul_f32 v[30:31], v[4:5], s[22:23] op_sel_hi:[1,0]
	s_nop 0
	v_exp_f32_e32 v30, v30
	v_exp_f32_e32 v31, v31
	s_nop 0
	v_pk_add_f32 v[30:31], v[30:31], 1.0 op_sel_hi:[1,0]
	s_nop 0
	v_rcp_f32_e32 v30, v30
	v_rcp_f32_e32 v31, v31
	s_nop 0
	v_pk_mul_f32 v[4:5], v[4:5], v[30:31]
	s_nop 0
	v_pk_mul_f32 v[4:5], v[26:27], v[4:5]
	v_pk_mul_f32 v[26:27], v[32:33], v[6:7] op_sel_hi:[1,0]
	v_add_u32_e32 v6, 32, v138
	v_pk_mul_f32 v[30:31], v[26:27], s[22:23] op_sel_hi:[1,0]
	v_cvt_pk_bf16_f32 v2, v4, v5
	v_mad_i64_i32 v[4:5], s[14:15], v6, s91, v[122:123]
	v_exp_f32_e32 v30, v30
	v_exp_f32_e32 v31, v31
	v_lshl_add_u64 v[4:5], v[4:5], 0, v[124:125]
	v_pk_add_f32 v[30:31], v[30:31], 1.0 op_sel_hi:[1,0]
	s_nop 0
	v_rcp_f32_e32 v30, v30
	v_rcp_f32_e32 v31, v31
	s_nop 0
	v_pk_mul_f32 v[26:27], v[26:27], v[30:31]
	s_nop 0
	v_pk_mul_f32 v[26:27], v[28:29], v[26:27]
	s_nop 0
	v_cvt_pk_bf16_f32 v3, v26, v27
	global_store_dwordx4 v[4:5], v[0:3], off sc1
	s_nop 1
	v_mov_b32_e32 v0, v7
	v_pk_mul_f32 v[2:3], v[22:23], v[0:1] op_sel_hi:[1,0]
	v_pk_mul_f32 v[4:5], v[16:17], v[0:1] op_sel_hi:[1,0]
	v_pk_mul_f32 v[6:7], v[2:3], s[22:23] op_sel_hi:[1,0]
	v_pk_mul_f32 v[8:9], v[8:9], v[0:1] op_sel_hi:[1,0]
	v_exp_f32_e32 v6, v6
	v_exp_f32_e32 v7, v7
	s_nop 0
	v_pk_add_f32 v[6:7], v[6:7], 1.0 op_sel_hi:[1,0]
	s_nop 0
	v_rcp_f32_e32 v6, v6
	v_rcp_f32_e32 v7, v7
	s_nop 0
	v_pk_mul_f32 v[2:3], v[2:3], v[6:7]
	s_nop 0
	v_pk_mul_f32 v[2:3], v[4:5], v[2:3]
	v_pk_mul_f32 v[4:5], v[24:25], v[0:1] op_sel_hi:[1,0]
	v_pk_mul_f32 v[6:7], v[18:19], v[0:1] op_sel_hi:[1,0]
	v_pk_mul_f32 v[16:17], v[4:5], s[22:23] op_sel_hi:[1,0]
	s_nop 0
	v_exp_f32_e32 v16, v16
	v_exp_f32_e32 v17, v17
	s_nop 0
	v_pk_add_f32 v[16:17], v[16:17], 1.0 op_sel_hi:[1,0]
	s_nop 0
	v_rcp_f32_e32 v16, v16
	v_rcp_f32_e32 v17, v17
	s_nop 0
	v_pk_mul_f32 v[4:5], v[4:5], v[16:17]
	s_nop 0
	v_pk_mul_f32 v[4:5], v[6:7], v[4:5]
	v_pk_mul_f32 v[6:7], v[12:13], v[0:1] op_sel_hi:[1,0]
	s_nop 0
	v_pk_mul_f32 v[12:13], v[6:7], s[22:23] op_sel_hi:[1,0]
	s_nop 0
	v_exp_f32_e32 v12, v12
	v_exp_f32_e32 v13, v13
	s_nop 0
	v_pk_add_f32 v[12:13], v[12:13], 1.0 op_sel_hi:[1,0]
	s_nop 0
	v_rcp_f32_e32 v12, v12
	v_rcp_f32_e32 v13, v13
	s_nop 0
	v_pk_mul_f32 v[6:7], v[6:7], v[12:13]
	s_nop 0
	v_pk_mul_f32 v[6:7], v[8:9], v[6:7]
	v_pk_mul_f32 v[8:9], v[14:15], v[0:1] op_sel_hi:[1,0]
	v_pk_mul_f32 v[0:1], v[10:11], v[0:1] op_sel_hi:[1,0]
	v_pk_mul_f32 v[10:11], v[8:9], s[22:23] op_sel_hi:[1,0]
	s_nop 0
	v_exp_f32_e32 v10, v10
	v_exp_f32_e32 v11, v11
	s_nop 0
	v_pk_add_f32 v[10:11], v[10:11], 1.0 op_sel_hi:[1,0]
	s_nop 0
	v_rcp_f32_e32 v10, v10
	v_rcp_f32_e32 v11, v11
	s_nop 0
	v_pk_mul_f32 v[8:9], v[8:9], v[10:11]
	v_add_u32_e32 v10, 48, v138
	v_pk_mul_f32 v[8:9], v[0:1], v[8:9]
	v_cvt_pk_bf16_f32 v0, v2, v3
	v_cvt_pk_bf16_f32 v1, v4, v5
	v_mad_i64_i32 v[4:5], s[14:15], v10, s91, v[122:123]
	v_lshl_add_u64 v[4:5], v[4:5], 0, v[124:125]
	s_mov_b64 s[14:15], -1
	v_cvt_pk_bf16_f32 v2, v6, v7
	v_cvt_pk_bf16_f32 v3, v8, v9
	global_store_dwordx4 v[4:5], v[0:3], off sc1
	s_cbranch_vccnz .LBB0_1590
	s_andn2_b64 vcc, exec, s[4:5]
	s_cbranch_vccnz .LBB0_1589
	s_barrier
	s_branch .LBB0_1589
